# P3: gate rows of the first three row groups fetched in front of each unit's K-loop (v222..v245 free there), handed to the epilogue by register copies
# speedup vs baseline: 1.0009x; 1.0009x over previous
;     __device__ __forceinline__ void operator()(PG8_ACC, const Unit& u, int wr, int wc, int fr, int fq) const {
;     ...
;         const bf16_t* GATE = GATE0 + (size_t)u.src * gstride; const int accum = u.src;
; #pragma unroll
;         for (int ai = 0; ai < 2; ++ai)
; #pragma unroll
;             for (int m = 0; m < 4; ++m) { const size_t off = (size_t)(row0 + ai * HALF + m * 16) * ldc + col0;
; #pragma unroll
;                 for (int bj = 0; bj < 2; ++bj) { const u32x4 gt = *(const u32x4*)(GATE + off + bj * HALF);
; template <class Epi, class Sched, bool ALIGN_EPI = false, bool SP2 = false>
; __device__ __forceinline__ void gemm_phase(PG8_LAS unsigned char* lds, const Gemm g, const Sched& S, const Epi& E, int wave_id) {
;     ...
; #pragma unroll
;         for (int a = 0; a < 2; ++a)
; #pragma unroll
;             for (int b = 0; b < 2; ++b)
; #pragma unroll
;                 for (int m = 0; m < 4; ++m)
; #pragma unroll
;                     for (int n = 0; n < 2; ++n) acc[a][b][m][n] = (f32x4){0.f, 0.f, 0.f, 0.f};
;         cur = nxt; cA = nA; cB = nB; ++ui;
.LBB0_520:
	s_add_u32 s5, s48, 0x100
	v_mov_b32_e32 v0, 0
	s_addc_u32 s26, s49, 0
	s_mov_b32 s27, -2
	v_mov_b32_e32 v1, v0
	v_mov_b32_e32 v2, v0
	v_mov_b32_e32 v3, v0
	v_mov_b32_e32 v4, v0
	v_mov_b32_e32 v5, v0
	v_mov_b32_e32 v6, v0
	v_mov_b32_e32 v7, v0
	v_mov_b32_e32 v16, v0
	v_mov_b32_e32 v17, v0
	v_mov_b32_e32 v18, v0
	v_mov_b32_e32 v19, v0
	v_mov_b32_e32 v20, v0
	v_mov_b32_e32 v21, v0
	v_mov_b32_e32 v22, v0
	v_mov_b32_e32 v23, v0
	v_mov_b32_e32 v32, v0
	v_mov_b32_e32 v33, v0
	v_mov_b32_e32 v34, v0
	v_mov_b32_e32 v35, v0
	v_mov_b32_e32 v36, v0
	v_mov_b32_e32 v37, v0
	v_mov_b32_e32 v38, v0
	v_mov_b32_e32 v39, v0
	v_mov_b32_e32 v48, v0
	v_mov_b32_e32 v49, v0
	v_mov_b32_e32 v50, v0
	v_mov_b32_e32 v51, v0
	v_mov_b32_e32 v52, v0
	v_mov_b32_e32 v53, v0
	v_mov_b32_e32 v54, v0
	v_mov_b32_e32 v55, v0
	v_mov_b32_e32 v8, v0
	v_mov_b32_e32 v9, v0
	v_mov_b32_e32 v10, v0
	v_mov_b32_e32 v11, v0
	v_mov_b32_e32 v12, v0
	v_mov_b32_e32 v13, v0
	v_mov_b32_e32 v14, v0
	v_mov_b32_e32 v15, v0
	v_mov_b32_e32 v24, v0
	v_mov_b32_e32 v25, v0
	v_mov_b32_e32 v26, v0
	v_mov_b32_e32 v27, v0
	v_mov_b32_e32 v28, v0
	v_mov_b32_e32 v29, v0
	v_mov_b32_e32 v30, v0
	v_mov_b32_e32 v31, v0
	v_mov_b32_e32 v40, v0
	v_mov_b32_e32 v41, v0
	v_mov_b32_e32 v42, v0
	v_mov_b32_e32 v43, v0
	v_mov_b32_e32 v44, v0
	v_mov_b32_e32 v45, v0
	v_mov_b32_e32 v46, v0
	v_mov_b32_e32 v47, v0
	v_mov_b32_e32 v56, v0
	v_mov_b32_e32 v57, v0
	v_mov_b32_e32 v58, v0
	v_mov_b32_e32 v59, v0
	v_mov_b32_e32 v60, v0
	v_mov_b32_e32 v61, v0
	v_mov_b32_e32 v62, v0
	v_mov_b32_e32 v63, v0
	v_mov_b32_e32 v64, v0
	v_mov_b32_e32 v65, v0
	v_mov_b32_e32 v66, v0
	v_mov_b32_e32 v67, v0
	v_mov_b32_e32 v68, v0
	v_mov_b32_e32 v69, v0
	v_mov_b32_e32 v70, v0
	v_mov_b32_e32 v71, v0
	v_mov_b32_e32 v80, v0
	v_mov_b32_e32 v81, v0
	v_mov_b32_e32 v82, v0
	v_mov_b32_e32 v83, v0
	v_mov_b32_e32 v84, v0
	v_mov_b32_e32 v85, v0
	v_mov_b32_e32 v86, v0
	v_mov_b32_e32 v87, v0
	v_mov_b32_e32 v96, v0
	v_mov_b32_e32 v97, v0
	v_mov_b32_e32 v98, v0
	v_mov_b32_e32 v99, v0
	v_mov_b32_e32 v100, v0
	v_mov_b32_e32 v101, v0
	v_mov_b32_e32 v102, v0
	v_mov_b32_e32 v103, v0
	v_mov_b32_e32 v112, v0
	v_mov_b32_e32 v113, v0
	v_mov_b32_e32 v114, v0
	v_mov_b32_e32 v115, v0
	v_mov_b32_e32 v116, v0
	v_mov_b32_e32 v117, v0
	v_mov_b32_e32 v118, v0
	v_mov_b32_e32 v119, v0
	v_mov_b32_e32 v72, v0
	v_mov_b32_e32 v73, v0
	v_mov_b32_e32 v74, v0
	v_mov_b32_e32 v75, v0
	v_mov_b32_e32 v76, v0
	v_mov_b32_e32 v77, v0
	v_mov_b32_e32 v78, v0
	v_mov_b32_e32 v79, v0
	v_mov_b32_e32 v88, v0
	v_mov_b32_e32 v89, v0
	v_mov_b32_e32 v90, v0
	v_mov_b32_e32 v91, v0
	v_mov_b32_e32 v92, v0
	v_mov_b32_e32 v93, v0
	v_mov_b32_e32 v94, v0
	v_mov_b32_e32 v95, v0
	v_mov_b32_e32 v104, v0
	v_mov_b32_e32 v105, v0
	v_mov_b32_e32 v106, v0
	v_mov_b32_e32 v107, v0
	v_mov_b32_e32 v108, v0
	v_mov_b32_e32 v109, v0
	v_mov_b32_e32 v110, v0
	v_mov_b32_e32 v111, v0
	v_mov_b32_e32 v120, v0
	v_mov_b32_e32 v121, v0
	v_mov_b32_e32 v122, v0
	v_mov_b32_e32 v123, v0
	v_mov_b32_e32 v124, v0
	v_mov_b32_e32 v125, v0
	v_mov_b32_e32 v126, v0
	v_mov_b32_e32 v127, v0
	s_lshl_b32 s100, s46, 11
	s_add_u32 s100, s20, s100
	s_addc_u32 s101, s21, 0
	v_lshl_or_b32 v246, s4, 8, v148
	v_lshl_add_u32 v248, s74, 8, v146
	v_ashrrev_i32_e32 v247, 31, v246
	v_mad_i64_i32 v[250:251], s[98:99], v248, s30, v[246:247]
	v_lshl_add_u64 v[250:251], v[250:251], 1, s[100:101]
	s_mov_b64 s[98:99], 0x34000
	global_load_dwordx4 v[222:225], v[250:251], off
	global_load_dwordx4 v[226:229], v[250:251], off offset:256
	v_lshl_add_u64 v[250:251], v[250:251], 0, s[98:99]
	global_load_dwordx4 v[230:233], v[250:251], off
	global_load_dwordx4 v[234:237], v[250:251], off offset:256
	v_lshl_add_u64 v[250:251], v[250:251], 0, s[98:99]
	global_load_dwordx4 v[238:241], v[250:251], off
	global_load_dwordx4 v[242:245], v[250:251], off offset:256

; __device__ __forceinline__ unsigned cvt_pk_bf16(float lo, float hi) { f32x2v_t v = {lo, hi}; bf16x2v_t b = __builtin_convertvector(v, bf16x2v_t); return __builtin_bit_cast(unsigned, b); }
;     __device__ __forceinline__ void operator()(PG8_ACC, const Unit& u, int wr, int wc, int fr, int fq) const {
;     ...
;         for (int ai = 0; ai < 2; ++ai)
; #pragma unroll
;             for (int m = 0; m < 4; ++m) { const size_t off = (size_t)(row0 + ai * HALF + m * 16) * ldc + col0;
; #pragma unroll
;                 for (int bj = 0; bj < 2; ++bj) { const u32x4 gt = *(const u32x4*)(GATE + off + bj * HALF);
;                     f32x4 a = acc[ai][bj][m][0], b = acc[ai][bj][m][1];
;                     a[0] *= bf_lo(gt.x); a[1] *= bf_hi(gt.x); a[2] *= bf_lo(gt.y); a[3] *= bf_hi(gt.y); b[0] *= bf_lo(gt.z); b[1] *= bf_hi(gt.z); b[2] *= bf_lo(gt.w); b[3] *= bf_hi(gt.w);
;                     if (accum) { const u32x4 mx = *(const u32x4*)(MIX + off + bj * HALF);
;                         a[0] += bf_lo(mx.x); a[1] += bf_hi(mx.x); a[2] += bf_lo(mx.y); a[3] += bf_hi(mx.y); b[0] += bf_lo(mx.z); b[1] += bf_hi(mx.z); b[2] += bf_lo(mx.w); b[3] += bf_hi(mx.w); }
;                     u32x4 w; w.x = cvt_pk_bf16(a[0], a[1]); w.y = cvt_pk_bf16(a[2], a[3]); w.z = cvt_pk_bf16(b[0], b[1]); w.w = cvt_pk_bf16(b[2], b[3]);
;                     *(u32x4*)(MIX + off + bj * HALF) = w; } }
.LBB0_524:
	s_ashr_i32 s47, s46, 31
	v_lshl_or_b32 v140, s4, 8, v148
	s_lshl_b64 s[4:5], s[46:47], 11
	s_add_u32 s44, s20, s4
	v_lshl_add_u32 v153, s74, 8, v146
	v_ashrrev_i32_e32 v141, 31, v140
	s_addc_u32 s45, s21, s5
	v_mad_i64_i32 v[158:159], s[4:5], v153, s30, v[140:141]
	v_lshl_add_u64 v[142:143], v[158:159], 1, s[44:45]
	s_nop 0
	s_cmp_lg_u32 s46, 0
	s_cselect_b64 s[48:49], -1, 0
	s_cmp_eq_u32 s46, 0
	s_waitcnt vmcnt(0)
	v_mov_b64_e32 v[154:155], v[222:223]
	v_mov_b64_e32 v[156:157], v[224:225]
	v_lshlrev_b32_e32 v144, 16, v154
	v_and_b32_e32 v145, 0xffff0000, v154
	v_lshlrev_b32_e32 v154, 16, v155
	v_and_b32_e32 v155, 0xffff0000, v155
	v_lshlrev_b32_e32 v160, 16, v156
	v_and_b32_e32 v161, 0xffff0000, v156
	v_lshlrev_b32_e32 v156, 16, v157
	v_and_b32_e32 v157, 0xffff0000, v157
	v_pk_mul_f32 v[124:125], v[124:125], v[144:145]
	v_pk_mul_f32 v[126:127], v[126:127], v[154:155]
	v_pk_mul_f32 v[144:145], v[120:121], v[160:161]
	v_pk_mul_f32 v[122:123], v[122:123], v[156:157]
	v_lshl_add_u64 v[120:121], v[158:159], 1, s[20:21]
	s_cbranch_scc1 .LBB0_526
	global_load_dwordx4 v[154:157], v[120:121], off
	s_waitcnt vmcnt(0)
	v_lshlrev_b32_e32 v158, 16, v154
	v_and_b32_e32 v159, 0xffff0000, v154
	v_lshlrev_b32_e32 v154, 16, v155
	v_and_b32_e32 v155, 0xffff0000, v155
	v_lshlrev_b32_e32 v160, 16, v156
	v_and_b32_e32 v161, 0xffff0000, v156
	v_lshlrev_b32_e32 v156, 16, v157
	v_and_b32_e32 v157, 0xffff0000, v157
	v_pk_add_f32 v[124:125], v[124:125], v[158:159]
	v_pk_add_f32 v[126:127], v[126:127], v[154:155]
	v_pk_add_f32 v[144:145], v[144:145], v[160:161]
	v_pk_add_f32 v[122:123], v[122:123], v[156:157]
.LBB0_526:
	v_mov_b64_e32 v[154:155], v[226:227]
	v_mov_b64_e32 v[156:157], v[228:229]
	v_cvt_pk_bf16_f32 v124, v124, v125
	v_cvt_pk_bf16_f32 v125, v126, v127
	v_cvt_pk_bf16_f32 v126, v144, v145
	v_cvt_pk_bf16_f32 v127, v122, v123
	v_cndmask_b32_e64 v122, 0, 1, s[48:49]
	global_store_dwordx4 v[120:121], v[124:127], off
	v_cmp_ne_u32_e64 s[4:5], 1, v122
	s_andn2_b64 vcc, exec, s[48:49]
	s_waitcnt vmcnt(1)
	v_lshlrev_b32_e32 v122, 16, v154
	v_and_b32_e32 v123, 0xffff0000, v154
	v_lshlrev_b32_e32 v124, 16, v155
	v_and_b32_e32 v125, 0xffff0000, v155
	v_lshlrev_b32_e32 v126, 16, v156
	v_and_b32_e32 v127, 0xffff0000, v156
	v_lshlrev_b32_e32 v142, 16, v157
	v_and_b32_e32 v143, 0xffff0000, v157
	v_pk_mul_f32 v[116:117], v[116:117], v[122:123]
	v_pk_mul_f32 v[118:119], v[118:119], v[124:125]
	v_pk_mul_f32 v[122:123], v[112:113], v[126:127]
	v_pk_mul_f32 v[112:113], v[114:115], v[142:143]
	s_cbranch_vccnz .LBB0_528
	global_load_dwordx4 v[124:127], v[120:121], off offset:256
	s_waitcnt vmcnt(0)
	v_lshlrev_b32_e32 v114, 16, v124
	v_and_b32_e32 v115, 0xffff0000, v124
	v_lshlrev_b32_e32 v124, 16, v125
	v_and_b32_e32 v125, 0xffff0000, v125
	v_lshlrev_b32_e32 v142, 16, v126
	v_and_b32_e32 v143, 0xffff0000, v126
	v_lshlrev_b32_e32 v126, 16, v127
	v_and_b32_e32 v127, 0xffff0000, v127
	v_pk_add_f32 v[116:117], v[116:117], v[114:115]
	v_pk_add_f32 v[118:119], v[118:119], v[124:125]
	v_pk_add_f32 v[122:123], v[122:123], v[142:143]
	v_pk_add_f32 v[112:113], v[112:113], v[126:127]
.LBB0_528:
	v_cvt_pk_bf16_f32 v114, v116, v117
	v_cvt_pk_bf16_f32 v117, v112, v113
	v_or_b32_e32 v112, 16, v153
	v_cvt_pk_bf16_f32 v115, v118, v119
	v_cvt_pk_bf16_f32 v116, v122, v123
	v_mad_i64_i32 v[118:119], s[26:27], v112, s30, v[140:141]
	global_store_dwordx4 v[120:121], v[114:117], off offset:256
	v_lshl_add_u64 v[112:113], v[118:119], 1, s[44:45]
	v_mov_b64_e32 v[114:115], v[230:231]
	v_mov_b64_e32 v[116:117], v[232:233]
	s_and_b64 vcc, exec, s[4:5]
	s_waitcnt vmcnt(0)
	v_lshlrev_b32_e32 v120, 16, v114
	v_and_b32_e32 v121, 0xffff0000, v114
	v_lshlrev_b32_e32 v114, 16, v115
	v_and_b32_e32 v115, 0xffff0000, v115
	v_lshlrev_b32_e32 v122, 16, v116
	v_and_b32_e32 v123, 0xffff0000, v116
	v_lshlrev_b32_e32 v116, 16, v117
	v_and_b32_e32 v117, 0xffff0000, v117
	v_pk_mul_f32 v[108:109], v[108:109], v[120:121]
	v_pk_mul_f32 v[110:111], v[110:111], v[114:115]
	v_pk_mul_f32 v[114:115], v[104:105], v[122:123]
	v_pk_mul_f32 v[106:107], v[106:107], v[116:117]
	v_lshl_add_u64 v[104:105], v[118:119], 1, s[20:21]
	s_cbranch_vccnz .LBB0_530
	global_load_dwordx4 v[116:119], v[104:105], off
	s_waitcnt vmcnt(0)
	v_lshlrev_b32_e32 v120, 16, v116
	v_and_b32_e32 v121, 0xffff0000, v116
	v_lshlrev_b32_e32 v116, 16, v117
	v_and_b32_e32 v117, 0xffff0000, v117
	v_lshlrev_b32_e32 v122, 16, v118
	v_and_b32_e32 v123, 0xffff0000, v118
	v_lshlrev_b32_e32 v118, 16, v119
	v_and_b32_e32 v119, 0xffff0000, v119
	v_pk_add_f32 v[108:109], v[108:109], v[120:121]
	v_pk_add_f32 v[110:111], v[110:111], v[116:117]
	v_pk_add_f32 v[114:115], v[114:115], v[122:123]
	v_pk_add_f32 v[106:107], v[106:107], v[118:119]
; __device__ __forceinline__ unsigned cvt_pk_bf16(float lo, float hi) { f32x2v_t v = {lo, hi}; bf16x2v_t b = __builtin_convertvector(v, bf16x2v_t); return __builtin_bit_cast(unsigned, b); }
;     __device__ __forceinline__ void operator()(PG8_ACC, const Unit& u, int wr, int wc, int fr, int fq) const {
;     ...
;         for (int ai = 0; ai < 2; ++ai)
; #pragma unroll
;             for (int m = 0; m < 4; ++m) { const size_t off = (size_t)(row0 + ai * HALF + m * 16) * ldc + col0;
; #pragma unroll
;                 for (int bj = 0; bj < 2; ++bj) { const u32x4 gt = *(const u32x4*)(GATE + off + bj * HALF);
;                     f32x4 a = acc[ai][bj][m][0], b = acc[ai][bj][m][1];
;                     a[0] *= bf_lo(gt.x); a[1] *= bf_hi(gt.x); a[2] *= bf_lo(gt.y); a[3] *= bf_hi(gt.y); b[0] *= bf_lo(gt.z); b[1] *= bf_hi(gt.z); b[2] *= bf_lo(gt.w); b[3] *= bf_hi(gt.w);
;                     if (accum) { const u32x4 mx = *(const u32x4*)(MIX + off + bj * HALF);
;                         a[0] += bf_lo(mx.x); a[1] += bf_hi(mx.x); a[2] += bf_lo(mx.y); a[3] += bf_hi(mx.y); b[0] += bf_lo(mx.z); b[1] += bf_hi(mx.z); b[2] += bf_lo(mx.w); b[3] += bf_hi(mx.w); }
;                     u32x4 w; w.x = cvt_pk_bf16(a[0], a[1]); w.y = cvt_pk_bf16(a[2], a[3]); w.z = cvt_pk_bf16(b[0], b[1]); w.w = cvt_pk_bf16(b[2], b[3]);
;                     *(u32x4*)(MIX + off + bj * HALF) = w; } }
.LBB0_530:
	v_mov_b64_e32 v[116:117], v[234:235]
	v_mov_b64_e32 v[118:119], v[236:237]
	v_cvt_pk_bf16_f32 v108, v108, v109
	v_cvt_pk_bf16_f32 v109, v110, v111
	v_cvt_pk_bf16_f32 v110, v114, v115
	v_cvt_pk_bf16_f32 v111, v106, v107
	global_store_dwordx4 v[104:105], v[108:111], off
	s_and_b64 vcc, exec, s[4:5]
	s_waitcnt vmcnt(1)
	v_lshlrev_b32_e32 v106, 16, v116
	v_and_b32_e32 v107, 0xffff0000, v116
	v_lshlrev_b32_e32 v108, 16, v117
	v_and_b32_e32 v109, 0xffff0000, v117
	v_lshlrev_b32_e32 v110, 16, v118
	v_and_b32_e32 v111, 0xffff0000, v118
	v_lshlrev_b32_e32 v112, 16, v119
	v_and_b32_e32 v113, 0xffff0000, v119
	v_pk_mul_f32 v[100:101], v[100:101], v[106:107]
	v_pk_mul_f32 v[102:103], v[102:103], v[108:109]
	v_pk_mul_f32 v[106:107], v[96:97], v[110:111]
	v_pk_mul_f32 v[96:97], v[98:99], v[112:113]
	s_cbranch_vccnz .LBB0_532
	global_load_dwordx4 v[108:111], v[104:105], off offset:256
	s_waitcnt vmcnt(0)
	v_lshlrev_b32_e32 v98, 16, v108
	v_and_b32_e32 v99, 0xffff0000, v108
	v_lshlrev_b32_e32 v108, 16, v109
	v_and_b32_e32 v109, 0xffff0000, v109
	v_lshlrev_b32_e32 v112, 16, v110
	v_and_b32_e32 v113, 0xffff0000, v110
	v_lshlrev_b32_e32 v110, 16, v111
	v_and_b32_e32 v111, 0xffff0000, v111
	v_pk_add_f32 v[100:101], v[100:101], v[98:99]
	v_pk_add_f32 v[102:103], v[102:103], v[108:109]
	v_pk_add_f32 v[106:107], v[106:107], v[112:113]
	v_pk_add_f32 v[96:97], v[96:97], v[110:111]
.LBB0_532:
	v_cvt_pk_bf16_f32 v98, v100, v101
	v_cvt_pk_bf16_f32 v101, v96, v97
	v_or_b32_e32 v96, 32, v153
	v_cvt_pk_bf16_f32 v99, v102, v103
	v_cvt_pk_bf16_f32 v100, v106, v107
	v_mad_i64_i32 v[102:103], s[26:27], v96, s30, v[140:141]
	global_store_dwordx4 v[104:105], v[98:101], off offset:256
	v_lshl_add_u64 v[96:97], v[102:103], 1, s[44:45]
	v_mov_b64_e32 v[98:99], v[238:239]
	v_mov_b64_e32 v[100:101], v[240:241]
	s_and_b64 vcc, exec, s[4:5]
	s_waitcnt vmcnt(0)
	v_lshlrev_b32_e32 v104, 16, v98
	v_and_b32_e32 v105, 0xffff0000, v98
	v_lshlrev_b32_e32 v98, 16, v99
	v_and_b32_e32 v99, 0xffff0000, v99
	v_lshlrev_b32_e32 v106, 16, v100
	v_and_b32_e32 v107, 0xffff0000, v100
	v_lshlrev_b32_e32 v100, 16, v101
	v_and_b32_e32 v101, 0xffff0000, v101
	v_pk_mul_f32 v[92:93], v[92:93], v[104:105]
	v_pk_mul_f32 v[94:95], v[94:95], v[98:99]
	v_pk_mul_f32 v[98:99], v[88:89], v[106:107]
	v_pk_mul_f32 v[90:91], v[90:91], v[100:101]
	v_lshl_add_u64 v[88:89], v[102:103], 1, s[20:21]
	s_cbranch_vccnz .LBB0_534
	global_load_dwordx4 v[100:103], v[88:89], off
	s_waitcnt vmcnt(0)
	v_lshlrev_b32_e32 v104, 16, v100
	v_and_b32_e32 v105, 0xffff0000, v100
	v_lshlrev_b32_e32 v100, 16, v101
	v_and_b32_e32 v101, 0xffff0000, v101
	v_lshlrev_b32_e32 v106, 16, v102
	v_and_b32_e32 v107, 0xffff0000, v102
	v_lshlrev_b32_e32 v102, 16, v103
	v_and_b32_e32 v103, 0xffff0000, v103
	v_pk_add_f32 v[92:93], v[92:93], v[104:105]
	v_pk_add_f32 v[94:95], v[94:95], v[100:101]
	v_pk_add_f32 v[98:99], v[98:99], v[106:107]
	v_pk_add_f32 v[90:91], v[90:91], v[102:103]
.LBB0_534:
	v_mov_b64_e32 v[100:101], v[242:243]
	v_mov_b64_e32 v[102:103], v[244:245]
	v_cvt_pk_bf16_f32 v92, v92, v93
	v_cvt_pk_bf16_f32 v93, v94, v95
	v_cvt_pk_bf16_f32 v94, v98, v99
	v_cvt_pk_bf16_f32 v95, v90, v91
	global_store_dwordx4 v[88:89], v[92:95], off
	s_and_b64 vcc, exec, s[4:5]
	s_waitcnt vmcnt(1)
	v_lshlrev_b32_e32 v90, 16, v100
	v_and_b32_e32 v91, 0xffff0000, v100
	v_lshlrev_b32_e32 v92, 16, v101
	v_and_b32_e32 v93, 0xffff0000, v101
	v_lshlrev_b32_e32 v94, 16, v102
	v_and_b32_e32 v95, 0xffff0000, v102
	v_lshlrev_b32_e32 v96, 16, v103
	v_and_b32_e32 v97, 0xffff0000, v103
	v_pk_mul_f32 v[84:85], v[84:85], v[90:91]
	v_pk_mul_f32 v[86:87], v[86:87], v[92:93]
	v_pk_mul_f32 v[90:91], v[80:81], v[94:95]
	v_pk_mul_f32 v[80:81], v[82:83], v[96:97]
	s_cbranch_vccnz .LBB0_536
	global_load_dwordx4 v[92:95], v[88:89], off offset:256
	s_waitcnt vmcnt(0)
	v_lshlrev_b32_e32 v82, 16, v92
	v_and_b32_e32 v83, 0xffff0000, v92
	v_lshlrev_b32_e32 v92, 16, v93
	v_and_b32_e32 v93, 0xffff0000, v93
	v_lshlrev_b32_e32 v96, 16, v94
	v_and_b32_e32 v97, 0xffff0000, v94
	v_lshlrev_b32_e32 v94, 16, v95
	v_and_b32_e32 v95, 0xffff0000, v95
	v_pk_add_f32 v[84:85], v[84:85], v[82:83]
	v_pk_add_f32 v[86:87], v[86:87], v[92:93]
	v_pk_add_f32 v[90:91], v[90:91], v[96:97]
	v_pk_add_f32 v[80:81], v[80:81], v[94:95]
